# attnA loop and everything after it shifted by 8 bytes (unexecuted pad): code-placement trial
# baseline (speedup 1.0000x reference)
; DI int ltid_w(int wave) { int t; asm volatile("v_mbcnt_lo_u32_b32 %0, -1, 0\n\tv_mbcnt_hi_u32_b32 %0, -1, %0" : "=v"(t)); return (wave << 6) | t; }
; template <int MODE>
; DI void attn_mfma(const Params& p, int l, int b, int hd, int qb, unsigned char* smem) {
;     ...
;   const int tid = ltid_w(p.wave), lane = tid & 63, wv = tid >> 6, r = lane & 31, h2 = lane >> 5;
;   const int mp = MODE ? 0 : (wv >> 1);
;   const bf16_t* P = (const bf16_t*)(p.ws + WS_P);
;   bf16_t* MIX = (bf16_t*)(p.ws + WS_HM);
;   const int kvh = MODE ? (hd >> 1) : hd;
;   const bf16_t* VT = MODE ? (const bf16_t*)(p.ws + WS_VTC) + ((size_t)(b * 2 + kvh) * 64) * NTOK : (const bf16_t*)(p.ws + WS_VTA) + ((size_t)(b * 4 + hd) * 64) * NTOK;
;   const int qcol = MODE ? C_Q + hd * 64 : A_Q + hd * 64;
;   const int kcol = MODE ? C_K + kvh * 64 : A_K + hd * 64;
;   unsigned char* sK = smem;
;   unsigned char* sV = smem + 8192;
;   const int tq = qb * QPB + (MODE ? wv : (wv & 1)) * 32 + r;
;   const size_t qrow = (size_t)b * NTOK + tq;
;   bf16x8 qf[KS];
; #pragma unroll
;   for (int ks = 0; ks < KS; ++ks) qf[ks] = *(const bf16x8*)(P + qrow * PW + qcol + (2 * (mp * 2 + ks) + h2) * 8);
;   const bool isctx = qb * QPB < NCTX;
;   int ntiles, band_lo = 0;
;   if (MODE == 0) ntiles = isctx ? 4 : 36;
;   else {
;     if (isctx) ntiles = 4;
;     else { const int i0 = qb * QPB - NCTX; int lo = i0 - 128; if (lo < 0) lo = 0; int hi = i0 + 256; if (hi > NLAT) hi = NLAT; band_lo = lo; ntiles = 4 + (hi - lo) / 64; }
;   }
;   const float cexp = (MODE ? 0.125f : 0.17677669529663687f) * 1.4426950408889634f;
;   float mrun = MODE ? p.sw_sink[l * 4 + hd] * 1.4426950408889634f : -1e30f;
;   float lsum = (MODE && h2 == 0) ? 1.f : 0.f;
;   f32x16 O[2];
; #pragma unroll
;   for (int vt = 0; vt < 2; ++vt)
; #pragma unroll
;     for (int i = 0; i < 16; ++i) O[vt][i] = 0.f;
;   const int lrow = tid >> 3, lc = tid & 7;
;   auto tile_base = [&](int j) -> int { return (MODE == 0 || j < 4) ? j * 64 : NCTX + band_lo + (j - 4) * 64; };
;   uint4 gk00, gk01, gk10, gk11, gv00, gv01, gv10, gv11;
;     ...
;   ATT_LOAD(tile_base(0), gk00, gk01, gv00, gv01);
;   ATT_LOAD(tile_base(1), gk10, gk11, gv10, gv11);
.LBB0_575:
	s_andn2_b64 vcc, exec, s[0:1]
	s_cbranch_vccnz .LBB0_591
	s_add_i32 s0, s46, 0xffc0
	s_and_b32 s8, s0, 0xffff
	s_mul_i32 s1, s8, 0xe38f
	s_lshr_b32 s5, s1, 21
	s_mul_i32 s1, s5, 36
	s_sub_i32 s2, s0, s1
	s_and_b32 s0, s2, 0xffff
	s_cmp_lt_u32 s0, 4
	v_readlane_b32 s6, v254, 12
	s_cselect_b64 s[0:1], -1, 0
	v_readlane_b32 s7, v254, 13
	s_and_b64 s[6:7], s[6:7], s[0:1]
	s_and_b64 vcc, exec, s[6:7]
	s_cbranch_vccnz .LBB0_591
	s_and_b32 s4, 0xffff, s5
	s_lshr_b32 s9, s4, 2
	s_and_b32 s6, s4, 3
	v_readlane_b32 s4, v253, 39
	s_add_u32 s10, s40, 0x41c6000
	v_mbcnt_lo_u32_b32 v6, -1, 0
	v_mbcnt_hi_u32_b32 v6, -1, v6
	s_addc_u32 s11, s41, 0
	v_or_b32_e32 v196, s4, v6
	s_lshl_b32 s4, s9, 8
	s_lshl_b32 s7, s6, 6
	s_or_b32 s4, s7, s4
	s_mulk_i32 s4, 0x1200
	s_add_u32 s4, s40, s4
	s_addc_u32 s13, s41, 0
	s_add_u32 s12, s4, 0xef06000
	s_addc_u32 s13, s13, 0
	s_lshl_b32 s2, s2, 6
	s_and_b32 s2, s2, 0xffc0
	v_lshrrev_b32_e32 v0, 1, v196
	s_mul_i32 s14, s9, 0x900
	v_and_b32_e32 v198, 31, v6
	v_and_b32_e32 v199, 32, v0
	s_add_i32 s2, s14, s2
	v_bfe_u32 v171, v6, 5, 1
	v_or3_b32 v165, v198, s2, v199
	v_ashrrev_i32_e32 v197, 7, v196
	v_mul_lo_u32 v160, v165, s33
	v_lshlrev_b32_e32 v164, 3, v171
	v_lshl_add_u64 v[166:167], s[10:11], 0, v[160:161]
	s_lshl_b32 s2, s6, 7
	v_lshl_or_b32 v2, v197, 5, v164
	v_lshl_add_u64 v[0:1], v[166:167], 0, s[2:3]
	v_ashrrev_i32_e32 v3, 31, v2
	v_lshl_add_u64 v[0:1], v[2:3], 1, v[0:1]
	v_ashrrev_i32_e32 v8, 3, v196
	s_waitcnt vmcnt(0)
	global_load_dwordx4 v[96:99], v[0:1], off
	global_load_dwordx4 v[100:103], v[0:1], off offset:32
	v_add_u32_e32 v7, s14, v8
	v_mov_b64_e32 v[0:1], s[10:11]
	v_lshlrev_b32_e32 v9, 4, v6
	s_and_b64 s[0:1], s[0:1], exec
	v_mad_i64_i32 v[2:3], s[0:1], v7, s33, v[0:1]
	v_and_b32_e32 v160, 0x70, v9
	s_cselect_b32 s4, 4, 36
	v_lshl_add_u64 v[4:5], v[2:3], 0, s[2:3]
	v_lshl_add_u64 v[2:3], v[2:3], 0, v[160:161]
	s_or_b32 s0, s2, 0x200
	s_mov_b32 s1, s3
	v_lshl_add_u64 v[2:3], v[2:3], 0, s[0:1]
	s_mov_b32 s14, 0x44000
	v_add_co_u32_e32 v2, vcc, s14, v2
	v_lshl_add_u64 v[4:5], v[4:5], 0, v[160:161]
	s_nop 0
	v_addc_co_u32_e32 v3, vcc, 0, v3, vcc
	global_load_dwordx4 v[104:107], v[4:5], off offset:512
	global_load_dwordx4 v[108:111], v[2:3], off offset:1024
	v_mov_b64_e32 v[2:3], s[12:13]
	v_add_u32_e32 v6, 32, v8
	v_mad_i64_i32 v[4:5], s[10:11], v8, s67, v[2:3]
	v_mad_i64_i32 v[2:3], s[10:11], v6, s67, v[2:3]
	v_add_u32_e32 v6, 64, v7
	v_mad_i64_i32 v[0:1], s[10:11], v6, s33, v[0:1]
	v_lshl_add_u64 v[6:7], v[0:1], 0, s[2:3]
	v_lshl_add_u64 v[0:1], v[0:1], 0, v[160:161]
	v_lshl_add_u64 v[0:1], v[0:1], 0, s[0:1]
	v_lshl_add_u64 v[6:7], v[6:7], 0, v[160:161]
	v_add_co_u32_e32 v0, vcc, s14, v0
	v_lshl_add_u64 v[4:5], v[4:5], 0, v[160:161]
	v_lshl_add_u64 v[2:3], v[2:3], 0, v[160:161]
	v_addc_co_u32_e32 v1, vcc, 0, v1, vcc
	global_load_dwordx4 v[112:115], v[6:7], off offset:512
	global_load_dwordx4 v[116:119], v[0:1], off offset:1024
	global_load_dwordx4 v[120:123], v[4:5], off
	global_load_dwordx4 v[124:127], v[4:5], off offset:128
	global_load_dwordx4 v[128:131], v[2:3], off
	global_load_dwordx4 v[132:135], v[2:3], off offset:128
	s_movk_i32 s0, 0x70
	v_bitop3_b32 v0, v196, s0, v9 bitop3:0x48
	s_movk_i32 s0, 0x88
	v_mul_lo_u32 v2, v8, s0
	s_mul_i32 s0, s9, 0x90000
	s_mul_i32 s1, s6, 0x24000
	s_add_i32 s0, s0, s1
	v_lshlrev_b32_e32 v1, 2, v197
	v_bfe_u32 v4, v196, 1, 3
	s_lshl_b32 s0, s0, 1
	v_lshl_or_b32 v141, v8, 7, v0
	v_lshlrev_b32_e32 v0, 7, v198
	v_or_b32_e32 v3, v1, v171
	v_bitop3_b32 v1, v1, v4, v171 bitop3:0x36
	s_add_u32 s0, s40, s0
	v_lshl_add_u32 v142, v1, 4, v0
	v_bitop3_b32 v1, v3, v4, 2 bitop3:0x36
	s_addc_u32 s1, s41, 0
	v_lshl_add_u32 v143, v1, 4, v0
	v_mov_b64_e32 v[0:1], s[0:1]
	s_mov_b64 s[12:13], s[0:1]
	s_and_b32 s5, s5, 3
	v_mbcnt_hi_u32_b32 v5, -1, v185
	v_mad_i64_i32 v[136:137], s[0:1], v8, s67, v[0:1]
	s_lshl_b32 s5, s5, 7
	v_and_b32_e32 v7, 64, v5
	s_mul_hi_u32 s0, s8, 0x1c71c72
	s_add_u32 s5, s40, s5
	v_xor_b32_e32 v6, 32, v5
	v_add_u32_e32 v7, 64, v7
	s_mul_hi_u32 s1, s0, 0x1332000
	s_mul_i32 s0, s0, 0x1332000
	s_addc_u32 s8, s41, 0
	v_cmp_lt_i32_e32 vcc, v6, v7
	s_add_u32 s0, s5, s0
	s_addc_u32 s1, s8, s1
	v_cndmask_b32_e32 v5, v5, v6, vcc
	v_lshlrev_b32_e32 v170, 2, v5
	v_mul_u32_u24_e32 v5, 0x88, v198
	v_mov_b64_e32 v[0:1], s[0:1]
	s_mov_b64 s[10:11], s[0:1]
	v_mov_b32_e32 v200, 0
	s_mov_b32 s2, 0
	v_mad_i64_i32 v[138:139], s[0:1], v8, s33, v[0:1]
	v_mov_b32_e32 v140, 0xf149f2ca
	v_add_u32_e32 v144, v2, v160
	v_mul_lo_u32 v156, v8, s33
	v_mul_lo_u32 v157, v8, s67
	v_add_u32_e32 v158, 0x2000, v144
	v_add_u32_e32 v159, 0x3100, v144
	v_add_u32_e32 v201, 0x6200, v144
	v_add_u32_e32 v202, 0x7300, v144
	v_add_u32_e32 v156, v156, v160
	v_add_u32_e32 v157, v157, v160
	v_add_u32_e32 v145, v164, v5
	v_add_u32_e32 v236, 0x2000, v145
	v_add_u32_e32 v237, 0x3000, v145
	v_add_u32_e32 v238, 0x6000, v145
	v_add_u32_e32 v239, 0x7000, v145
	v_mov_b32_e32 v16, 0
	v_mov_b32_e32 v17, v200
	v_mov_b32_e32 v18, v200
	v_mov_b32_e32 v19, v200
	v_mov_b32_e32 v20, v200
	v_mov_b32_e32 v21, v200
	v_mov_b32_e32 v22, v200
	v_mov_b32_e32 v23, v200
	v_mov_b32_e32 v24, v200
	v_mov_b32_e32 v25, v200
	v_mov_b32_e32 v26, v200
	v_mov_b32_e32 v27, v200
	v_mov_b32_e32 v28, v200
	v_mov_b32_e32 v29, v200
	v_mov_b32_e32 v30, v200
	v_mov_b32_e32 v31, v200
	v_mov_b32_e32 v0, v200
	v_mov_b32_e32 v1, v200
	v_mov_b32_e32 v2, v200
	v_mov_b32_e32 v3, v200
	v_mov_b32_e32 v4, v200
	v_mov_b32_e32 v5, v200
	v_mov_b32_e32 v6, v200
	v_mov_b32_e32 v7, v200
	v_mov_b32_e32 v8, v200
	v_mov_b32_e32 v9, v200
	v_mov_b32_e32 v10, v200
	v_mov_b32_e32 v11, v200
	v_mov_b32_e32 v12, v200
	v_mov_b32_e32 v13, v200
	v_mov_b32_e32 v14, v200
	v_mov_b32_e32 v15, v200
	s_branch .LBB0_580
	s_nop 0
	s_nop 0
